# v20: v15 plus grid-barrier followers poll the top-level generation word directly instead of waiting for their XCD leader to relay it (one hop less per barrier)
# speedup vs baseline: 1.0044x; 1.0044x over previous
; DI unsigned xb_ld(unsigned* p)              { return __hip_atomic_load(p, __ATOMIC_RELAXED, __HIP_MEMORY_SCOPE_AGENT); }
; DI unsigned xb_add(unsigned* p, unsigned v) { return __hip_atomic_fetch_add(p, v, __ATOMIC_RELAXED, __HIP_MEMORY_SCOPE_AGENT); }
; #define XB_SPIN(cond, bar) do { unsigned _sp = 0; while (cond) { __builtin_amdgcn_s_sleep(1); \
;     if ((++_sp & 255u) == 0u) { if (xb_ld(&(bar)[XB_TMO])) break; if (_sp > XB_SPIN_CAP) { atomicAdd(&(bar)[XB_TMO], 1u); break; } } } } while (0)
; DI void xcd_barrier(const XcdBarrier& b) {
;     ...
;     const unsigned old = xb_add(&bar[XB_XSUB(b.x)], 1u);
;     const unsigned gen = old / nloc;
;     if (old + 1u == (gen + 1u) * nloc) {
;       __builtin_amdgcn_fence(__ATOMIC_RELEASE, "agent");
;       asm volatile("s_waitcnt vmcnt(0)" ::: "memory");
;       const unsigned og = xb_add(&bar[XB_TOP], 1u);
;       const unsigned tg = og / nx;
;       if (og + 1u == (tg + 1u) * nx) xb_add(&bar[XB_TOPGEN], 1u);
;       else XB_SPIN(xb_ld(&bar[XB_TOPGEN]) == tg, bar);
;       __builtin_amdgcn_fence(__ATOMIC_ACQUIRE, "agent");
;       xb_add(&bar[XB_XGEN(b.x)], 1u);
;       asm volatile("s_waitcnt vmcnt(0)" ::: "memory");
;     } else {
;       XB_SPIN(xb_ld(&bar[XB_XGEN(b.x)]) == gen, bar);
;       __builtin_amdgcn_fence(__ATOMIC_ACQUIRE, "agent");
;       asm volatile("s_waitcnt vmcnt(0)" ::: "memory");
;     }
.LBB0_253:
	global_atomic_add v4, v[148:149], v194, off sc0
	v_cvt_f32_u32_e32 v0, v3
	v_sub_u32_e32 v5, 0, v3
	v_rcp_iflag_f32_e32 v0, v0
	s_nop 0
	v_mul_f32_e32 v0, 0x4f7ffffe, v0
	v_cvt_u32_f32_e32 v0, v0
	v_mul_lo_u32 v5, v5, v0
	v_mul_hi_u32 v5, v0, v5
	v_add_u32_e32 v0, v0, v5
	s_waitcnt vmcnt(0)
	v_mul_hi_u32 v0, v4, v0
	v_mul_lo_u32 v5, v0, v3
	v_sub_u32_e32 v5, v4, v5
	v_add_u32_e32 v6, 1, v0
	v_cmp_ge_u32_e32 vcc, v5, v3
	v_add_u32_e32 v4, 1, v4
	s_nop 0
	v_cndmask_b32_e32 v0, v0, v6, vcc
	v_sub_u32_e32 v6, v5, v3
	v_cndmask_b32_e32 v5, v5, v6, vcc
	v_add_u32_e32 v6, 1, v0
	v_cmp_ge_u32_e32 vcc, v5, v3
	s_nop 1
	v_cndmask_b32_e32 v0, v0, v6, vcc
	v_mul_lo_u32 v5, v3, v0
	v_add_u32_e32 v3, v5, v3
	v_cmp_ne_u32_e32 vcc, v4, v3
	s_and_saveexec_b64 s[2:3], vcc
	s_xor_b64 s[2:3], exec, s[2:3]
	s_cbranch_execz .LBB0_267
	s_waitcnt lgkmcnt(0)
	v_readlane_b32 s4, v252, 53
	v_readlane_b32 s5, v252, 54
	s_nop 4
	global_load_dword v2, v1, s[4:5] sc1
	s_waitcnt vmcnt(0)
	v_cmp_eq_u32_e32 vcc, v2, v0
	s_and_saveexec_b64 s[4:5], vcc
	s_cbranch_execz .LBB0_266
	s_mov_b32 s16, 1
	s_mov_b64 s[6:7], 0
	s_branch .LBB0_257

; DI unsigned xb_ld(unsigned* p)              { return __hip_atomic_load(p, __ATOMIC_RELAXED, __HIP_MEMORY_SCOPE_AGENT); }
; DI unsigned xb_add(unsigned* p, unsigned v) { return __hip_atomic_fetch_add(p, v, __ATOMIC_RELAXED, __HIP_MEMORY_SCOPE_AGENT); }
; #define XB_SPIN(cond, bar) do { unsigned _sp = 0; while (cond) { __builtin_amdgcn_s_sleep(1); \
;     if ((++_sp & 255u) == 0u) { if (xb_ld(&(bar)[XB_TMO])) break; if (_sp > XB_SPIN_CAP) { atomicAdd(&(bar)[XB_TMO], 1u); break; } } } } while (0)
; DI void xcd_barrier(const XcdBarrier& b) {
;     ...
;       else XB_SPIN(xb_ld(&bar[XB_TOPGEN]) == tg, bar);
;       __builtin_amdgcn_fence(__ATOMIC_ACQUIRE, "agent");
;       xb_add(&bar[XB_XGEN(b.x)], 1u);
;       asm volatile("s_waitcnt vmcnt(0)" ::: "memory");
;     } else {
;       XB_SPIN(xb_ld(&bar[XB_XGEN(b.x)]) == gen, bar);
.LBB0_259:
	v_readlane_b32 s12, v252, 53
	v_readlane_b32 s13, v252, 54
	s_nop 4
	global_load_dword v2, v1, s[12:13] sc1
	s_add_i32 s16, s16, 1
	s_mov_b64 s[12:13], -1
	s_waitcnt vmcnt(0)
	v_cmp_ne_u32_e32 vcc, v2, v0
	s_orn2_b64 s[10:11], vcc, exec
	s_branch .LBB0_256

; DI unsigned xb_ld(unsigned* p)              { return __hip_atomic_load(p, __ATOMIC_RELAXED, __HIP_MEMORY_SCOPE_AGENT); }
; DI unsigned xb_add(unsigned* p, unsigned v) { return __hip_atomic_fetch_add(p, v, __ATOMIC_RELAXED, __HIP_MEMORY_SCOPE_AGENT); }
; #define XB_SPIN(cond, bar) do { unsigned _sp = 0; while (cond) { __builtin_amdgcn_s_sleep(1); \
;     if ((++_sp & 255u) == 0u) { if (xb_ld(&(bar)[XB_TMO])) break; if (_sp > XB_SPIN_CAP) { atomicAdd(&(bar)[XB_TMO], 1u); break; } } } } while (0)
; DI void xcd_barrier(const XcdBarrier& b) {
;     ...
;     const unsigned old = xb_add(&bar[XB_XSUB(b.x)], 1u);
;     const unsigned gen = old / nloc;
;     if (old + 1u == (gen + 1u) * nloc) {
;       __builtin_amdgcn_fence(__ATOMIC_RELEASE, "agent");
;       asm volatile("s_waitcnt vmcnt(0)" ::: "memory");
;       const unsigned og = xb_add(&bar[XB_TOP], 1u);
;       const unsigned tg = og / nx;
;       if (og + 1u == (tg + 1u) * nx) xb_add(&bar[XB_TOPGEN], 1u);
;       else XB_SPIN(xb_ld(&bar[XB_TOPGEN]) == tg, bar);
;       __builtin_amdgcn_fence(__ATOMIC_ACQUIRE, "agent");
;       xb_add(&bar[XB_XGEN(b.x)], 1u);
;       asm volatile("s_waitcnt vmcnt(0)" ::: "memory");
;     } else {
;       XB_SPIN(xb_ld(&bar[XB_XGEN(b.x)]) == gen, bar);
;       __builtin_amdgcn_fence(__ATOMIC_ACQUIRE, "agent");
;       asm volatile("s_waitcnt vmcnt(0)" ::: "memory");
;     }
.LBB0_383:
	global_atomic_add v4, v[148:149], v194, off sc0
	v_cvt_f32_u32_e32 v0, v3
	v_sub_u32_e32 v5, 0, v3
	v_rcp_iflag_f32_e32 v0, v0
	s_nop 0
	v_mul_f32_e32 v0, 0x4f7ffffe, v0
	v_cvt_u32_f32_e32 v0, v0
	v_mul_lo_u32 v5, v5, v0
	v_mul_hi_u32 v5, v0, v5
	v_add_u32_e32 v0, v0, v5
	s_waitcnt vmcnt(0)
	v_mul_hi_u32 v0, v4, v0
	v_mul_lo_u32 v5, v0, v3
	v_sub_u32_e32 v5, v4, v5
	v_add_u32_e32 v6, 1, v0
	v_cmp_ge_u32_e32 vcc, v5, v3
	v_add_u32_e32 v4, 1, v4
	s_nop 0
	v_cndmask_b32_e32 v0, v0, v6, vcc
	v_sub_u32_e32 v6, v5, v3
	v_cndmask_b32_e32 v5, v5, v6, vcc
	v_add_u32_e32 v6, 1, v0
	v_cmp_ge_u32_e32 vcc, v5, v3
	s_nop 1
	v_cndmask_b32_e32 v0, v0, v6, vcc
	v_mul_lo_u32 v5, v3, v0
	v_add_u32_e32 v3, v5, v3
	v_cmp_ne_u32_e32 vcc, v4, v3
	s_and_saveexec_b64 s[2:3], vcc
	s_xor_b64 s[2:3], exec, s[2:3]
	s_cbranch_execz .LBB0_397
	s_waitcnt lgkmcnt(0)
	v_readlane_b32 s4, v252, 53
	v_readlane_b32 s5, v252, 54
	s_nop 4
	global_load_dword v2, v1, s[4:5] sc1
	s_waitcnt vmcnt(0)
	v_cmp_eq_u32_e32 vcc, v2, v0
	s_and_saveexec_b64 s[4:5], vcc
	s_cbranch_execz .LBB0_396
	s_mov_b32 s17, 1
	s_mov_b64 s[6:7], 0
	s_branch .LBB0_387

; DI unsigned xb_ld(unsigned* p)              { return __hip_atomic_load(p, __ATOMIC_RELAXED, __HIP_MEMORY_SCOPE_AGENT); }
; DI unsigned xb_add(unsigned* p, unsigned v) { return __hip_atomic_fetch_add(p, v, __ATOMIC_RELAXED, __HIP_MEMORY_SCOPE_AGENT); }
; #define XB_SPIN(cond, bar) do { unsigned _sp = 0; while (cond) { __builtin_amdgcn_s_sleep(1); \
;     if ((++_sp & 255u) == 0u) { if (xb_ld(&(bar)[XB_TMO])) break; if (_sp > XB_SPIN_CAP) { atomicAdd(&(bar)[XB_TMO], 1u); break; } } } } while (0)
; DI void xcd_barrier(const XcdBarrier& b) {
;     ...
;       else XB_SPIN(xb_ld(&bar[XB_TOPGEN]) == tg, bar);
;       __builtin_amdgcn_fence(__ATOMIC_ACQUIRE, "agent");
;       xb_add(&bar[XB_XGEN(b.x)], 1u);
;       asm volatile("s_waitcnt vmcnt(0)" ::: "memory");
;     } else {
;       XB_SPIN(xb_ld(&bar[XB_XGEN(b.x)]) == gen, bar);
.LBB0_389:
	v_readlane_b32 s12, v252, 53
	v_readlane_b32 s13, v252, 54
	s_nop 4
	global_load_dword v2, v1, s[12:13] sc1
	s_add_i32 s17, s17, 1
	s_mov_b64 s[12:13], -1
	s_waitcnt vmcnt(0)
	v_cmp_ne_u32_e32 vcc, v2, v0
	s_orn2_b64 s[10:11], vcc, exec
	s_branch .LBB0_386

; DI unsigned xb_ld(unsigned* p)              { return __hip_atomic_load(p, __ATOMIC_RELAXED, __HIP_MEMORY_SCOPE_AGENT); }
; DI unsigned xb_add(unsigned* p, unsigned v) { return __hip_atomic_fetch_add(p, v, __ATOMIC_RELAXED, __HIP_MEMORY_SCOPE_AGENT); }
; #define XB_SPIN(cond, bar) do { unsigned _sp = 0; while (cond) { __builtin_amdgcn_s_sleep(1); \
;     if ((++_sp & 255u) == 0u) { if (xb_ld(&(bar)[XB_TMO])) break; if (_sp > XB_SPIN_CAP) { atomicAdd(&(bar)[XB_TMO], 1u); break; } } } } while (0)
; DI void xcd_barrier(const XcdBarrier& b) {
;     ...
;     const unsigned old = xb_add(&bar[XB_XSUB(b.x)], 1u);
;     const unsigned gen = old / nloc;
;     if (old + 1u == (gen + 1u) * nloc) {
;       __builtin_amdgcn_fence(__ATOMIC_RELEASE, "agent");
;       asm volatile("s_waitcnt vmcnt(0)" ::: "memory");
;       const unsigned og = xb_add(&bar[XB_TOP], 1u);
;       const unsigned tg = og / nx;
;       if (og + 1u == (tg + 1u) * nx) xb_add(&bar[XB_TOPGEN], 1u);
;       else XB_SPIN(xb_ld(&bar[XB_TOPGEN]) == tg, bar);
;       __builtin_amdgcn_fence(__ATOMIC_ACQUIRE, "agent");
;       xb_add(&bar[XB_XGEN(b.x)], 1u);
;       asm volatile("s_waitcnt vmcnt(0)" ::: "memory");
;     } else {
;       XB_SPIN(xb_ld(&bar[XB_XGEN(b.x)]) == gen, bar);
;       __builtin_amdgcn_fence(__ATOMIC_ACQUIRE, "agent");
;       asm volatile("s_waitcnt vmcnt(0)" ::: "memory");
;     }
.LBB0_781:
	global_atomic_add v4, v[148:149], v194, off sc0
	v_cvt_f32_u32_e32 v0, v3
	v_sub_u32_e32 v5, 0, v3
	v_rcp_iflag_f32_e32 v0, v0
	s_nop 0
	v_mul_f32_e32 v0, 0x4f7ffffe, v0
	v_cvt_u32_f32_e32 v0, v0
	v_mul_lo_u32 v5, v5, v0
	v_mul_hi_u32 v5, v0, v5
	v_add_u32_e32 v0, v0, v5
	s_waitcnt vmcnt(0)
	v_mul_hi_u32 v0, v4, v0
	v_mul_lo_u32 v5, v0, v3
	v_sub_u32_e32 v5, v4, v5
	v_add_u32_e32 v6, 1, v0
	v_cmp_ge_u32_e32 vcc, v5, v3
	v_add_u32_e32 v4, 1, v4
	s_nop 0
	v_cndmask_b32_e32 v0, v0, v6, vcc
	v_sub_u32_e32 v6, v5, v3
	v_cndmask_b32_e32 v5, v5, v6, vcc
	v_add_u32_e32 v6, 1, v0
	v_cmp_ge_u32_e32 vcc, v5, v3
	s_nop 1
	v_cndmask_b32_e32 v0, v0, v6, vcc
	v_mul_lo_u32 v5, v3, v0
	v_add_u32_e32 v3, v5, v3
	v_cmp_ne_u32_e32 vcc, v4, v3
	s_and_saveexec_b64 s[2:3], vcc
	s_xor_b64 s[2:3], exec, s[2:3]
	s_cbranch_execz .LBB0_795
	s_waitcnt lgkmcnt(0)
	v_readlane_b32 s4, v252, 53
	v_readlane_b32 s5, v252, 54
	s_nop 4
	global_load_dword v2, v1, s[4:5] sc1
	s_waitcnt vmcnt(0)
	v_cmp_eq_u32_e32 vcc, v2, v0
	s_and_saveexec_b64 s[4:5], vcc
	s_cbranch_execz .LBB0_794
	s_mov_b32 s18, 1
	s_mov_b64 s[8:9], 0
	s_branch .LBB0_785

; DI unsigned xb_ld(unsigned* p)              { return __hip_atomic_load(p, __ATOMIC_RELAXED, __HIP_MEMORY_SCOPE_AGENT); }
; DI unsigned xb_add(unsigned* p, unsigned v) { return __hip_atomic_fetch_add(p, v, __ATOMIC_RELAXED, __HIP_MEMORY_SCOPE_AGENT); }
; #define XB_SPIN(cond, bar) do { unsigned _sp = 0; while (cond) { __builtin_amdgcn_s_sleep(1); \
;     if ((++_sp & 255u) == 0u) { if (xb_ld(&(bar)[XB_TMO])) break; if (_sp > XB_SPIN_CAP) { atomicAdd(&(bar)[XB_TMO], 1u); break; } } } } while (0)
; DI void xcd_barrier(const XcdBarrier& b) {
;     ...
;       else XB_SPIN(xb_ld(&bar[XB_TOPGEN]) == tg, bar);
;       __builtin_amdgcn_fence(__ATOMIC_ACQUIRE, "agent");
;       xb_add(&bar[XB_XGEN(b.x)], 1u);
;       asm volatile("s_waitcnt vmcnt(0)" ::: "memory");
;     } else {
;       XB_SPIN(xb_ld(&bar[XB_XGEN(b.x)]) == gen, bar);
.LBB0_787:
	v_readlane_b32 s14, v252, 53
	v_readlane_b32 s15, v252, 54
	s_nop 4
	global_load_dword v2, v1, s[14:15] sc1
	s_add_i32 s18, s18, 1
	s_mov_b64 s[14:15], -1
	s_waitcnt vmcnt(0)
	v_cmp_ne_u32_e32 vcc, v2, v0
	s_orn2_b64 s[12:13], vcc, exec
	s_branch .LBB0_784
